# GEMM units: first k-loop iteration peeled with inline-0 SrcC on each accumulator's first MFMA; the 128 per-unit accumulator zeroing moves removed
# baseline (speedup 1.0000x reference)
; #define PG8_STAGE(bufoff, gbase, voff) do { _Pragma("unroll") for (int _i = 0; _i < 2; ++_i) \
;         __builtin_amdgcn_global_load_lds((const unsigned*)((const char*)(gbase) + (voff)[_i]), (PG8_LAS unsigned*)(lds + (bufoff) + ldsw + _i * 8192), 16, 0, 0); } while (0)
; #define PG8_LDA(dst, b, h) do { _Pragma("unroll") for (int m = 0; m < 4; ++m) _Pragma("unroll") for (int k = 0; k < 2; ++k) dst[m][k] = *(const PG8_LAS bf16x8*)(lds + PG8_SA(b, h) + aoff + m * 2048 + k * 1024); } while (0)
; #define PG8_LDB(dst, b, h) do { _Pragma("unroll") for (int n = 0; n < 2; ++n) _Pragma("unroll") for (int k = 0; k < 2; ++k) dst[n][k] = *(const PG8_LAS bf16x8*)(lds + PG8_SB(b, h) + boff + n * 2048 + k * 1024); } while (0)
; #define PG8_MMA(ai, bj, At, Bt) do { __builtin_amdgcn_s_setprio(1); _Pragma("unroll") for (int m = 0; m < 4; ++m) _Pragma("unroll") for (int n = 0; n < 2; ++n) _Pragma("unroll") for (int k = 0; k < 2; ++k) \
;         acc[ai][bj][m][n] = __builtin_amdgcn_mfma_f32_16x16x32_bf16(Bt[n][k], At[m][k], acc[ai][bj][m][n], 0, 0, 0); __builtin_amdgcn_s_setprio(0); } while (0)
; template <class Epi, class Sched, bool ALIGN_EPI = false, bool SP2 = false>
; __device__ __forceinline__ void gemm_phase(PG8_LAS unsigned char* lds, const Gemm g, const Sched& S, const Epi& E, int wv) {
;     ...
;             if constexpr (SP2) {
;             PG8_LDB(B0, 0, 0); PG8_LDB(B1, 0, 1); PG8_SCHED; PG8_LDA(At, 0, 0); PG8_STAGE(PG8_SA(1, 1), a1 + hstep, voffA);
;             PG8_WAIT_V(8); PG8_WAIT_L(0); PG8_BAR; PG8_MMA(0, 0, At, B0); PG8_MMA(0, 1, At, B1); PG8_BAR; PG8_SCHED;
;             PG8_LDA(At, 0, 1); PG8_STAGE(PG8_SB(0, 0), b2, voffB); PG8_STAGE(PG8_SB(0, 1), b2 + hstep, voffB); PG8_STAGE(PG8_SA(0, 0), a2, voffA);
;             PG8_WAIT_V(8); PG8_WAIT_L(0); PG8_BAR; PG8_MMA(1, 0, At, B0); PG8_MMA(1, 1, At, B1); PG8_BAR; PG8_SCHED;
;             PG8_LDB(B0, 1, 0); PG8_LDB(B1, 1, 1); PG8_SCHED; PG8_LDA(At, 1, 0); PG8_STAGE(PG8_SA(0, 1), a2 + hstep, voffA);
;             PG8_WAIT_V(8); PG8_WAIT_L(0); PG8_BAR; PG8_MMA(0, 0, At, B0); PG8_MMA(0, 1, At, B1); PG8_BAR; PG8_SCHED;
;             PG8_LDA(At, 1, 1); PG8_STAGE(PG8_SB(1, 0), b3, voffB); PG8_STAGE(PG8_SB(1, 1), b3 + hstep, voffB); PG8_STAGE(PG8_SA(1, 0), a3, voffA);
;             PG8_WAIT_V(8); PG8_WAIT_L(0); PG8_BAR; PG8_MMA(1, 0, At, B0); PG8_MMA(1, 1, At, B1); PG8_BAR; PG8_SCHED;
.LBB0_119:
	s_ashr_i32 s21, s20, 31
	s_lshl_b64 s[38:39], s[20:21], 20
	s_add_u32 s38, s64, s38
	s_addc_u32 s39, s65, s39
	s_and_b64 s[40:41], s[36:37], exec
	s_cselect_b32 s7, s39, s35
	s_cselect_b32 s21, s38, s34
	s_ashr_i32 s19, s18, 31
	s_lshl_b64 s[40:41], s[18:19], 20
	s_add_u32 s40, s1, s40
	s_addc_u32 s41, s2, s41
	s_and_b64 s[46:47], s[36:37], exec
	s_cselect_b32 s19, s41, s45
	s_cselect_b32 s48, s40, s44
	s_add_u32 s34, s34, 0x80080
	s_addc_u32 s35, s35, 0
	s_add_u32 s49, s44, 0x100
	s_addc_u32 s50, s45, 0
	s_mov_b32 s51, -2
	s_add_u32 s44, s34, 0xfff80080
	s_addc_u32 s45, s35, -1
	s_add_i32 s52, 0, 0x10000
	s_cmp_eq_u32 s51, 28
	s_cselect_b32 s47, s7, s45
	s_cselect_b32 s46, s21, s44
	s_cselect_b32 s45, s19, s50
	s_cselect_b32 s44, s48, s49
	s_add_i32 s54, 0, 0x14000
	v_add_u32_e32 v152, s52, v189
	v_add_u32_e32 v168, s54, v189
	ds_read_b128 v[128:131], v152
	ds_read_b128 v[132:135], v152 offset:1024
	ds_read_b128 v[148:151], v152 offset:2048
	ds_read_b128 v[152:155], v152 offset:3072
	s_nop 0
	ds_read_b128 v[156:159], v168
	ds_read_b128 v[160:163], v168 offset:1024
	ds_read_b128 v[164:167], v168 offset:2048
	ds_read_b128 v[168:171], v168 offset:3072
	s_add_i32 m0, s11, 0xc000
	ds_read_b128 v[172:175], v192
	ds_read_b128 v[194:197], v192 offset:1024
	ds_read_b128 v[198:201], v192 offset:2048
	ds_read_b128 v[202:205], v192 offset:3072
	ds_read_b128 v[206:209], v192 offset:4096
	ds_read_b128 v[210:213], v192 offset:5120
	ds_read_b128 v[214:217], v192 offset:6144
	ds_read_b128 v[218:221], v192 offset:7168
	global_load_lds_dwordx4 v144, s[34:35]
	s_add_i32 m0, s11, 0xe000
	s_nop 0
	global_load_lds_dwordx4 v146, s[34:35]
	s_waitcnt vmcnt(8)
	s_waitcnt lgkmcnt(0)
	s_barrier
	s_setprio 1
	s_waitcnt lgkmcnt(0)
	v_mfma_f32_16x16x32_bf16 v[124:127], v[128:131], v[172:175], 0
	v_mfma_f32_16x16x32_bf16 v[120:123], v[148:151], v[172:175], 0
	v_mfma_f32_16x16x32_bf16 v[112:115], v[128:131], v[198:201], 0
	v_mfma_f32_16x16x32_bf16 v[104:107], v[148:151], v[198:201], 0
	v_mfma_f32_16x16x32_bf16 v[96:99], v[128:131], v[206:209], 0
	v_mfma_f32_16x16x32_bf16 v[88:91], v[148:151], v[206:209], 0
	v_mfma_f32_16x16x32_bf16 v[80:83], v[128:131], v[214:217], 0
	v_mfma_f32_16x16x32_bf16 v[72:75], v[148:151], v[214:217], 0
	v_mfma_f32_16x16x32_bf16 v[124:127], v[132:135], v[194:197], v[124:127]
	v_mfma_f32_16x16x32_bf16 v[120:123], v[152:155], v[194:197], v[120:123]
	v_mfma_f32_16x16x32_bf16 v[112:115], v[132:135], v[202:205], v[112:115]
	v_mfma_f32_16x16x32_bf16 v[104:107], v[152:155], v[202:205], v[104:107]
	v_mfma_f32_16x16x32_bf16 v[96:99], v[132:135], v[210:213], v[96:99]
	v_mfma_f32_16x16x32_bf16 v[88:91], v[152:155], v[210:213], v[88:91]
	v_mfma_f32_16x16x32_bf16 v[80:83], v[132:135], v[218:221], v[80:83]
	v_mfma_f32_16x16x32_bf16 v[72:75], v[152:155], v[218:221], v[72:75]
	s_setprio 0
	s_setprio 1
	v_mfma_f32_16x16x32_bf16 v[116:119], v[156:159], v[172:175], 0
	v_mfma_f32_16x16x32_bf16 v[108:111], v[164:167], v[172:175], 0
	v_mfma_f32_16x16x32_bf16 v[100:103], v[156:159], v[198:201], 0
	v_mfma_f32_16x16x32_bf16 v[92:95], v[164:167], v[198:201], 0
	v_mfma_f32_16x16x32_bf16 v[84:87], v[156:159], v[206:209], 0
	v_mfma_f32_16x16x32_bf16 v[76:79], v[164:167], v[206:209], 0
	v_mfma_f32_16x16x32_bf16 v[68:71], v[156:159], v[214:217], 0
	v_mfma_f32_16x16x32_bf16 v[64:67], v[164:167], v[214:217], 0
	v_mfma_f32_16x16x32_bf16 v[116:119], v[160:163], v[194:197], v[116:119]
	v_mfma_f32_16x16x32_bf16 v[108:111], v[168:171], v[194:197], v[108:111]
	v_mfma_f32_16x16x32_bf16 v[100:103], v[160:163], v[202:205], v[100:103]
	v_mfma_f32_16x16x32_bf16 v[92:95], v[168:171], v[202:205], v[92:95]
	v_mfma_f32_16x16x32_bf16 v[84:87], v[160:163], v[210:213], v[84:87]
	v_mfma_f32_16x16x32_bf16 v[76:79], v[168:171], v[210:213], v[76:79]
	v_mfma_f32_16x16x32_bf16 v[68:71], v[160:163], v[218:221], v[68:71]
	v_mfma_f32_16x16x32_bf16 v[64:67], v[168:171], v[218:221], v[64:67]
	s_setprio 0
	s_barrier
	s_add_i32 s52, s52, s0
	s_mov_b32 m0, s52
	ds_read_b128 v[172:175], v192 offset:16384
	ds_read_b128 v[194:197], v192 offset:17408
	ds_read_b128 v[198:201], v192 offset:18432
	ds_read_b128 v[202:205], v192 offset:19456
	ds_read_b128 v[206:209], v192 offset:20480
	ds_read_b128 v[210:213], v192 offset:21504
	ds_read_b128 v[214:217], v192 offset:22528
	ds_read_b128 v[218:221], v192 offset:23552
	global_load_lds_dwordx4 v176, s[44:45]
	s_add_i32 m0, s52, 0x2000
	s_add_u32 s52, s44, 0x80000
	s_addc_u32 s53, s45, 0
	s_add_i32 s54, s54, s0
	global_load_lds_dwordx4 v136, s[44:45]
	s_mov_b32 m0, s54
	v_lshl_add_u64 v[184:185], s[46:47], 0, v[138:139]
	global_load_lds_dwordx4 v176, s[52:53]
	s_add_i32 m0, s54, 0x2000
	s_nop 0
	global_load_lds_dwordx4 v136, s[52:53]
	v_lshl_add_u64 v[182:183], s[46:47], 0, v[140:141]
	s_mov_b32 m0, s11
	s_nop 0
	global_load_lds_dwordx4 v[182:183], off
	s_mov_b32 m0, s22
	s_nop 0
	global_load_lds_dwordx4 v[184:185], off
	s_waitcnt vmcnt(8)
	s_waitcnt lgkmcnt(0)
	s_barrier
; #define PG8_STAGE(bufoff, gbase, voff) do { _Pragma("unroll") for (int _i = 0; _i < 2; ++_i) \
;         __builtin_amdgcn_global_load_lds((const unsigned*)((const char*)(gbase) + (voff)[_i]), (PG8_LAS unsigned*)(lds + (bufoff) + ldsw + _i * 8192), 16, 0, 0); } while (0)
; #define PG8_LDA(dst, b, h) do { _Pragma("unroll") for (int m = 0; m < 4; ++m) _Pragma("unroll") for (int k = 0; k < 2; ++k) dst[m][k] = *(const PG8_LAS bf16x8*)(lds + PG8_SA(b, h) + aoff + m * 2048 + k * 1024); } while (0)
; #define PG8_LDB(dst, b, h) do { _Pragma("unroll") for (int n = 0; n < 2; ++n) _Pragma("unroll") for (int k = 0; k < 2; ++k) dst[n][k] = *(const PG8_LAS bf16x8*)(lds + PG8_SB(b, h) + boff + n * 2048 + k * 1024); } while (0)
; #define PG8_MMA(ai, bj, At, Bt) do { __builtin_amdgcn_s_setprio(1); _Pragma("unroll") for (int m = 0; m < 4; ++m) _Pragma("unroll") for (int n = 0; n < 2; ++n) _Pragma("unroll") for (int k = 0; k < 2; ++k) \
;         acc[ai][bj][m][n] = __builtin_amdgcn_mfma_f32_16x16x32_bf16(Bt[n][k], At[m][k], acc[ai][bj][m][n], 0, 0, 0); __builtin_amdgcn_s_setprio(0); } while (0)
; #define PG8_WAIT_V(n) asm volatile("s_waitcnt vmcnt(" #n ")" ::: "memory")
; #define PG8_WAIT_L(n) asm volatile("s_waitcnt lgkmcnt(" #n ")" ::: "memory")
; #define PG8_BAR __builtin_amdgcn_s_barrier()
; #define PG8_SCHED __builtin_amdgcn_sched_barrier(0)
; template <class Epi, class Sched, bool ALIGN_EPI = false, bool SP2 = false>
; __device__ __forceinline__ void gemm_phase(PG8_LAS unsigned char* lds, const Gemm g, const Sched& S, const Epi& E, int wv) {
;     ...
;             PG8_WAIT_V(8); PG8_WAIT_L(0); PG8_BAR; PG8_MMA(0, 0, At, B0); PG8_MMA(0, 1, At, B1); PG8_BAR; PG8_SCHED;
;             PG8_LDA(At, 0, 1); PG8_STAGE(PG8_SB(0, 0), b2, voffB); PG8_STAGE(PG8_SB(0, 1), b2 + hstep, voffB); PG8_STAGE(PG8_SA(0, 0), a2, voffA);
;             PG8_WAIT_V(8); PG8_WAIT_L(0); PG8_BAR; PG8_MMA(1, 0, At, B0); PG8_MMA(1, 1, At, B1); PG8_BAR; PG8_SCHED;
;             PG8_LDB(B0, 1, 0); PG8_LDB(B1, 1, 1); PG8_SCHED; PG8_LDA(At, 1, 0); PG8_STAGE(PG8_SA(0, 1), a2 + hstep, voffA);
;             PG8_WAIT_V(8); PG8_WAIT_L(0); PG8_BAR; PG8_MMA(0, 0, At, B0); PG8_MMA(0, 1, At, B1); PG8_BAR; PG8_SCHED;
	s_setprio 1
	s_waitcnt lgkmcnt(0)
	v_mfma_f32_16x16x32_bf16 v[60:63], v[128:131], v[172:175], 0
	v_mfma_f32_16x16x32_bf16 v[56:59], v[148:151], v[172:175], 0
	v_mfma_f32_16x16x32_bf16 v[48:51], v[128:131], v[198:201], 0
	v_mfma_f32_16x16x32_bf16 v[40:43], v[148:151], v[198:201], 0
	v_mfma_f32_16x16x32_bf16 v[32:35], v[128:131], v[206:209], 0
	v_mfma_f32_16x16x32_bf16 v[24:27], v[148:151], v[206:209], 0
	v_mfma_f32_16x16x32_bf16 v[16:19], v[128:131], v[214:217], 0
	v_mfma_f32_16x16x32_bf16 v[8:11], v[148:151], v[214:217], 0
	v_mfma_f32_16x16x32_bf16 v[60:63], v[132:135], v[194:197], v[60:63]
	v_mfma_f32_16x16x32_bf16 v[56:59], v[152:155], v[194:197], v[56:59]
	v_mfma_f32_16x16x32_bf16 v[48:51], v[132:135], v[202:205], v[48:51]
	v_mfma_f32_16x16x32_bf16 v[40:43], v[152:155], v[202:205], v[40:43]
	v_mfma_f32_16x16x32_bf16 v[32:35], v[132:135], v[210:213], v[32:35]
	v_mfma_f32_16x16x32_bf16 v[24:27], v[152:155], v[210:213], v[24:27]
	v_mfma_f32_16x16x32_bf16 v[16:19], v[132:135], v[218:221], v[16:19]
	v_mfma_f32_16x16x32_bf16 v[8:11], v[152:155], v[218:221], v[8:11]
	s_setprio 0
	s_setprio 1
	v_mfma_f32_16x16x32_bf16 v[52:55], v[156:159], v[172:175], 0
	v_mfma_f32_16x16x32_bf16 v[44:47], v[164:167], v[172:175], 0
	v_mfma_f32_16x16x32_bf16 v[36:39], v[156:159], v[198:201], 0
	v_mfma_f32_16x16x32_bf16 v[28:31], v[164:167], v[198:201], 0
	v_mfma_f32_16x16x32_bf16 v[20:23], v[156:159], v[206:209], 0
	v_mfma_f32_16x16x32_bf16 v[12:15], v[164:167], v[206:209], 0
	v_mfma_f32_16x16x32_bf16 v[4:7], v[156:159], v[214:217], 0
	v_mfma_f32_16x16x32_bf16 v[0:3], v[164:167], v[214:217], 0
	v_mfma_f32_16x16x32_bf16 v[52:55], v[160:163], v[194:197], v[52:55]
	v_mfma_f32_16x16x32_bf16 v[44:47], v[168:171], v[194:197], v[44:47]
	v_mfma_f32_16x16x32_bf16 v[36:39], v[160:163], v[202:205], v[36:39]
	v_mfma_f32_16x16x32_bf16 v[28:31], v[168:171], v[202:205], v[28:31]
	v_mfma_f32_16x16x32_bf16 v[20:23], v[160:163], v[210:213], v[20:23]
	v_mfma_f32_16x16x32_bf16 v[12:15], v[168:171], v[210:213], v[12:15]
	v_mfma_f32_16x16x32_bf16 v[4:7], v[160:163], v[218:221], v[4:7]
	v_mfma_f32_16x16x32_bf16 v[0:3], v[168:171], v[218:221], v[0:3]
	s_setprio 0
	s_barrier
	s_add_i32 s52, 0, 0x18000
	s_add_i32 s53, 0, 0x1c000
	v_add_u32_e32 v152, s52, v189
	v_add_u32_e32 v168, s53, v189
	ds_read_b128 v[128:131], v152
	ds_read_b128 v[132:135], v152 offset:1024
	ds_read_b128 v[148:151], v152 offset:2048
	ds_read_b128 v[152:155], v152 offset:3072
	ds_read_b128 v[156:159], v168
	ds_read_b128 v[160:163], v168 offset:1024
	ds_read_b128 v[164:167], v168 offset:2048
	ds_read_b128 v[168:171], v168 offset:3072
	s_add_u32 s46, s46, 0x80000
	s_addc_u32 s47, s47, 0
	s_mov_b32 m0, s23
	ds_read_b128 v[172:175], v192 offset:32768
	ds_read_b128 v[194:197], v192 offset:33792
	ds_read_b128 v[198:201], v192 offset:34816
	ds_read_b128 v[202:205], v192 offset:35840
	ds_read_b128 v[206:209], v192 offset:36864
	ds_read_b128 v[210:213], v192 offset:37888
	ds_read_b128 v[214:217], v192 offset:38912
	ds_read_b128 v[218:221], v192 offset:39936
	global_load_lds_dwordx4 v140, s[46:47]
	v_lshl_add_u64 v[186:187], s[46:47], 0, v[138:139]
	s_mov_b32 m0, s24
	s_nop 0
	global_load_lds_dwordx4 v[186:187], off
	s_waitcnt vmcnt(8)
	s_waitcnt lgkmcnt(0)
	s_barrier
	s_setprio 1
	s_waitcnt lgkmcnt(0)
	v_mfma_f32_16x16x32_bf16 v[124:127], v[128:131], v[172:175], v[124:127]
	v_mfma_f32_16x16x32_bf16 v[120:123], v[148:151], v[172:175], v[120:123]
	v_mfma_f32_16x16x32_bf16 v[112:115], v[128:131], v[198:201], v[112:115]
	v_mfma_f32_16x16x32_bf16 v[104:107], v[148:151], v[198:201], v[104:107]
	v_mfma_f32_16x16x32_bf16 v[96:99], v[128:131], v[206:209], v[96:99]
	v_mfma_f32_16x16x32_bf16 v[88:91], v[148:151], v[206:209], v[88:91]
	v_mfma_f32_16x16x32_bf16 v[80:83], v[128:131], v[214:217], v[80:83]
	v_mfma_f32_16x16x32_bf16 v[72:75], v[148:151], v[214:217], v[72:75]
	v_mfma_f32_16x16x32_bf16 v[124:127], v[132:135], v[194:197], v[124:127]
	v_mfma_f32_16x16x32_bf16 v[120:123], v[152:155], v[194:197], v[120:123]
	v_mfma_f32_16x16x32_bf16 v[112:115], v[132:135], v[202:205], v[112:115]
	v_mfma_f32_16x16x32_bf16 v[104:107], v[152:155], v[202:205], v[104:107]
	v_mfma_f32_16x16x32_bf16 v[96:99], v[132:135], v[210:213], v[96:99]
	v_mfma_f32_16x16x32_bf16 v[88:91], v[152:155], v[210:213], v[88:91]
	v_mfma_f32_16x16x32_bf16 v[80:83], v[132:135], v[218:221], v[80:83]
	v_mfma_f32_16x16x32_bf16 v[72:75], v[152:155], v[218:221], v[72:75]
	s_setprio 0
	s_setprio 1
	v_mfma_f32_16x16x32_bf16 v[116:119], v[156:159], v[172:175], v[116:119]
	v_mfma_f32_16x16x32_bf16 v[108:111], v[164:167], v[172:175], v[108:111]
	v_mfma_f32_16x16x32_bf16 v[100:103], v[156:159], v[198:201], v[100:103]
	v_mfma_f32_16x16x32_bf16 v[92:95], v[164:167], v[198:201], v[92:95]
	v_mfma_f32_16x16x32_bf16 v[84:87], v[156:159], v[206:209], v[84:87]
	v_mfma_f32_16x16x32_bf16 v[76:79], v[164:167], v[206:209], v[76:79]
	v_mfma_f32_16x16x32_bf16 v[68:71], v[156:159], v[214:217], v[68:71]
	v_mfma_f32_16x16x32_bf16 v[64:67], v[164:167], v[214:217], v[64:67]
	v_mfma_f32_16x16x32_bf16 v[116:119], v[160:163], v[194:197], v[116:119]
	v_mfma_f32_16x16x32_bf16 v[108:111], v[168:171], v[194:197], v[108:111]
	v_mfma_f32_16x16x32_bf16 v[100:103], v[160:163], v[202:205], v[100:103]
	v_mfma_f32_16x16x32_bf16 v[92:95], v[168:171], v[202:205], v[92:95]
	v_mfma_f32_16x16x32_bf16 v[84:87], v[160:163], v[210:213], v[84:87]
	v_mfma_f32_16x16x32_bf16 v[76:79], v[168:171], v[210:213], v[76:79]
	v_mfma_f32_16x16x32_bf16 v[68:71], v[160:163], v[218:221], v[68:71]
	v_mfma_f32_16x16x32_bf16 v[64:67], v[168:171], v[218:221], v[64:67]
	s_setprio 0
	s_barrier
; #define PG8_STAGE(bufoff, gbase, voff) do { _Pragma("unroll") for (int _i = 0; _i < 2; ++_i) \
;         __builtin_amdgcn_global_load_lds((const unsigned*)((const char*)(gbase) + (voff)[_i]), (PG8_LAS unsigned*)(lds + (bufoff) + ldsw + _i * 8192), 16, 0, 0); } while (0)
; #define PG8_LDA(dst, b, h) do { _Pragma("unroll") for (int m = 0; m < 4; ++m) _Pragma("unroll") for (int k = 0; k < 2; ++k) dst[m][k] = *(const PG8_LAS bf16x8*)(lds + PG8_SA(b, h) + aoff + m * 2048 + k * 1024); } while (0)
; #define PG8_MMA(ai, bj, At, Bt) do { __builtin_amdgcn_s_setprio(1); _Pragma("unroll") for (int m = 0; m < 4; ++m) _Pragma("unroll") for (int n = 0; n < 2; ++n) _Pragma("unroll") for (int k = 0; k < 2; ++k) \
;         acc[ai][bj][m][n] = __builtin_amdgcn_mfma_f32_16x16x32_bf16(Bt[n][k], At[m][k], acc[ai][bj][m][n], 0, 0, 0); __builtin_amdgcn_s_setprio(0); } while (0)
; #define PG8_WAIT_V(n) asm volatile("s_waitcnt vmcnt(" #n ")" ::: "memory")
; #define PG8_WAIT_L(n) asm volatile("s_waitcnt lgkmcnt(" #n ")" ::: "memory")
; #define PG8_BAR __builtin_amdgcn_s_barrier()
; #define PG8_SCHED __builtin_amdgcn_sched_barrier(0)
; template <class Epi, class Sched, bool ALIGN_EPI = false, bool SP2 = false>
; __device__ __forceinline__ void gemm_phase(PG8_LAS unsigned char* lds, const Gemm g, const Sched& S, const Epi& E, int wv) {
;     ...
;         for (int t = 0; t < nt; t += 2) {
;             const bool last = (t == nt - 2);
;             const char* a1 = cA + (size_t)(t + 1) * kstep;
;     ...
;             PG8_LDA(At, 1, 1); PG8_STAGE(PG8_SB(1, 0), b3, voffB); PG8_STAGE(PG8_SB(1, 1), b3 + hstep, voffB); PG8_STAGE(PG8_SA(1, 0), a3, voffA);
;             PG8_WAIT_V(8); PG8_WAIT_L(0); PG8_BAR; PG8_MMA(1, 0, At, B0); PG8_MMA(1, 1, At, B1); PG8_BAR; PG8_SCHED;
	s_add_i32 s46, s52, s0
	s_add_u32 s100, s44, s28
	s_addc_u32 s101, s45, s29
	s_mov_b32 m0, s46
	ds_read_b128 v[172:175], v192 offset:49152
	ds_read_b128 v[194:197], v192 offset:50176
	ds_read_b128 v[198:201], v192 offset:51200
	ds_read_b128 v[202:205], v192 offset:52224
	ds_read_b128 v[206:209], v192 offset:53248
	ds_read_b128 v[210:213], v192 offset:54272
	ds_read_b128 v[214:217], v192 offset:55296
	ds_read_b128 v[218:221], v192 offset:56320
	global_load_lds_dwordx4 v176, s[100:101]
	s_add_i32 m0, s46, 0x2000
	s_add_u32 s44, s44, 0x80080
	s_addc_u32 s45, s45, 0
	s_add_i32 s46, s53, s0
	global_load_lds_dwordx4 v136, s[100:101]
	s_mov_b32 m0, s46
	s_nop 0
	global_load_lds_dwordx4 v176, s[44:45]
	s_add_i32 m0, s46, 0x2000
	s_nop 0
	global_load_lds_dwordx4 v136, s[44:45]
	v_lshl_add_u64 v[178:179], v[182:183], 0, s[28:29]
	s_mov_b32 m0, s25
	s_nop 0
	global_load_lds_dwordx4 v[178:179], off
	v_lshl_add_u64 v[178:179], v[184:185], 0, s[28:29]
	s_mov_b32 m0, s27
	s_nop 0
	global_load_lds_dwordx4 v[178:179], off
	s_waitcnt vmcnt(8)
	s_waitcnt lgkmcnt(0)
	s_barrier
	s_setprio 1
	s_waitcnt lgkmcnt(0)
	v_mfma_f32_16x16x32_bf16 v[60:63], v[128:131], v[172:175], v[60:63]
	v_mfma_f32_16x16x32_bf16 v[56:59], v[148:151], v[172:175], v[56:59]
	v_mfma_f32_16x16x32_bf16 v[48:51], v[128:131], v[198:201], v[48:51]
	v_mfma_f32_16x16x32_bf16 v[40:43], v[148:151], v[198:201], v[40:43]
	v_mfma_f32_16x16x32_bf16 v[32:35], v[128:131], v[206:209], v[32:35]
	v_mfma_f32_16x16x32_bf16 v[24:27], v[148:151], v[206:209], v[24:27]
	v_mfma_f32_16x16x32_bf16 v[16:19], v[128:131], v[214:217], v[16:19]
	v_mfma_f32_16x16x32_bf16 v[8:11], v[148:151], v[214:217], v[8:11]
	v_mfma_f32_16x16x32_bf16 v[60:63], v[132:135], v[194:197], v[60:63]
	v_mfma_f32_16x16x32_bf16 v[56:59], v[152:155], v[194:197], v[56:59]
	v_mfma_f32_16x16x32_bf16 v[48:51], v[132:135], v[202:205], v[48:51]
	v_mfma_f32_16x16x32_bf16 v[40:43], v[152:155], v[202:205], v[40:43]
	v_mfma_f32_16x16x32_bf16 v[32:35], v[132:135], v[210:213], v[32:35]
	v_mfma_f32_16x16x32_bf16 v[24:27], v[152:155], v[210:213], v[24:27]
	v_mfma_f32_16x16x32_bf16 v[16:19], v[132:135], v[218:221], v[16:19]
	v_mfma_f32_16x16x32_bf16 v[8:11], v[152:155], v[218:221], v[8:11]
	s_setprio 0
	s_setprio 1
	v_mfma_f32_16x16x32_bf16 v[52:55], v[156:159], v[172:175], v[52:55]
	v_mfma_f32_16x16x32_bf16 v[44:47], v[164:167], v[172:175], v[44:47]
	v_mfma_f32_16x16x32_bf16 v[36:39], v[156:159], v[198:201], v[36:39]
	v_mfma_f32_16x16x32_bf16 v[28:31], v[164:167], v[198:201], v[28:31]
	v_mfma_f32_16x16x32_bf16 v[20:23], v[156:159], v[206:209], v[20:23]
	v_mfma_f32_16x16x32_bf16 v[12:15], v[164:167], v[206:209], v[12:15]
	v_mfma_f32_16x16x32_bf16 v[4:7], v[156:159], v[214:217], v[4:7]
	v_mfma_f32_16x16x32_bf16 v[0:3], v[164:167], v[214:217], v[0:3]
	v_mfma_f32_16x16x32_bf16 v[52:55], v[160:163], v[194:197], v[52:55]
	v_mfma_f32_16x16x32_bf16 v[44:47], v[168:171], v[194:197], v[44:47]
	v_mfma_f32_16x16x32_bf16 v[36:39], v[160:163], v[202:205], v[36:39]
	v_mfma_f32_16x16x32_bf16 v[28:31], v[168:171], v[202:205], v[28:31]
	v_mfma_f32_16x16x32_bf16 v[20:23], v[160:163], v[210:213], v[20:23]
	v_mfma_f32_16x16x32_bf16 v[12:15], v[168:171], v[210:213], v[12:15]
	v_mfma_f32_16x16x32_bf16 v[4:7], v[160:163], v[218:221], v[4:7]
	v_mfma_f32_16x16x32_bf16 v[0:3], v[168:171], v[218:221], v[0:3]
	s_setprio 0
	s_barrier
	s_add_i32 s51, s51, 2
	s_add_u32 s34, s34, 0x100
	s_addc_u32 s35, s35, 0
	s_add_u32 s49, s49, 0x100
	s_addc_u32 s50, s50, 0
	s_cmp_gt_u32 s51, 29

; #define PG8_STAGE(bufoff, gbase, voff) do { _Pragma("unroll") for (int _i = 0; _i < 2; ++_i) \
;         __builtin_amdgcn_global_load_lds((const unsigned*)((const char*)(gbase) + (voff)[_i]), (PG8_LAS unsigned*)(lds + (bufoff) + ldsw + _i * 8192), 16, 0, 0); } while (0)
; #define PG8_LDA(dst, b, h) do { _Pragma("unroll") for (int m = 0; m < 4; ++m) _Pragma("unroll") for (int k = 0; k < 2; ++k) dst[m][k] = *(const PG8_LAS bf16x8*)(lds + PG8_SA(b, h) + aoff + m * 2048 + k * 1024); } while (0)
; #define PG8_LDB(dst, b, h) do { _Pragma("unroll") for (int n = 0; n < 2; ++n) _Pragma("unroll") for (int k = 0; k < 2; ++k) dst[n][k] = *(const PG8_LAS bf16x8*)(lds + PG8_SB(b, h) + boff + n * 2048 + k * 1024); } while (0)
; #define PG8_MMA(ai, bj, At, Bt) do { __builtin_amdgcn_s_setprio(1); _Pragma("unroll") for (int m = 0; m < 4; ++m) _Pragma("unroll") for (int n = 0; n < 2; ++n) _Pragma("unroll") for (int k = 0; k < 2; ++k) \
;         acc[ai][bj][m][n] = __builtin_amdgcn_mfma_f32_16x16x32_bf16(Bt[n][k], At[m][k], acc[ai][bj][m][n], 0, 0, 0); __builtin_amdgcn_s_setprio(0); } while (0)
; template <class Epi, class Sched, bool ALIGN_EPI = false, bool SP2 = false>
; __device__ __forceinline__ void gemm_phase(PG8_LAS unsigned char* lds, const Gemm g, const Sched& S, const Epi& E, int wv) {
;     ...
;             if constexpr (SP2) {
;             PG8_LDB(B0, 0, 0); PG8_LDB(B1, 0, 1); PG8_SCHED; PG8_LDA(At, 0, 0); PG8_STAGE(PG8_SA(1, 1), a1 + hstep, voffA);
;             PG8_WAIT_V(8); PG8_WAIT_L(0); PG8_BAR; PG8_MMA(0, 0, At, B0); PG8_MMA(0, 1, At, B1); PG8_BAR; PG8_SCHED;
;             PG8_LDA(At, 0, 1); PG8_STAGE(PG8_SB(0, 0), b2, voffB); PG8_STAGE(PG8_SB(0, 1), b2 + hstep, voffB); PG8_STAGE(PG8_SA(0, 0), a2, voffA);
;             PG8_WAIT_V(8); PG8_WAIT_L(0); PG8_BAR; PG8_MMA(1, 0, At, B0); PG8_MMA(1, 1, At, B1); PG8_BAR; PG8_SCHED;
;             PG8_LDB(B0, 1, 0); PG8_LDB(B1, 1, 1); PG8_SCHED; PG8_LDA(At, 1, 0); PG8_STAGE(PG8_SA(0, 1), a2 + hstep, voffA);
;             PG8_WAIT_V(8); PG8_WAIT_L(0); PG8_BAR; PG8_MMA(0, 0, At, B0); PG8_MMA(0, 1, At, B1); PG8_BAR; PG8_SCHED;
;             PG8_LDA(At, 1, 1); PG8_STAGE(PG8_SB(1, 0), b3, voffB); PG8_STAGE(PG8_SB(1, 1), b3 + hstep, voffB); PG8_STAGE(PG8_SA(1, 0), a3, voffA);
;             PG8_WAIT_V(8); PG8_WAIT_L(0); PG8_BAR; PG8_MMA(1, 0, At, B0); PG8_MMA(1, 1, At, B1); PG8_BAR; PG8_SCHED;
.LBB0_342:
	s_ashr_i32 s21, s20, 31
	s_lshl_b64 s[44:45], s[20:21], 20
	s_add_u32 s44, s82, s44
	s_addc_u32 s45, s83, s45
	s_and_b64 s[46:47], s[38:39], exec
	s_cselect_b32 s7, s45, s41
	s_cselect_b32 s21, s44, s40
	s_ashr_i32 s19, s18, 31
	s_lshl_b64 s[46:47], s[18:19], 20
	s_add_u32 s46, s0, s46
	s_addc_u32 s47, s1, s47
	s_and_b64 s[50:51], s[38:39], exec
	s_cselect_b32 s19, s47, s49
	s_cselect_b32 s35, s46, s48
	s_add_u32 s40, s40, 0x80080
	s_addc_u32 s41, s41, 0
	s_add_u32 s52, s48, 0x100
	s_addc_u32 s53, s49, 0
	s_mov_b32 s54, -2
	s_add_u32 s48, s40, 0xfff80080
	s_addc_u32 s49, s41, -1
	s_add_i32 s55, 0, 0x10000
	s_cmp_eq_u32 s54, 28
	s_cselect_b32 s51, s7, s49
	s_cselect_b32 s50, s21, s48
	s_cselect_b32 s49, s19, s53
	s_cselect_b32 s48, s35, s52
	s_add_i32 s58, 0, 0x14000
	v_add_u32_e32 v154, s55, v147
	v_add_u32_e32 v170, s58, v147
	ds_read_b128 v[138:141], v154
	ds_read_b128 v[142:145], v154 offset:1024
	ds_read_b128 v[150:153], v154 offset:2048
	s_nop 0
	ds_read_b128 v[154:157], v154 offset:3072
	ds_read_b128 v[158:161], v170
	ds_read_b128 v[162:165], v170 offset:1024
	ds_read_b128 v[166:169], v170 offset:2048
	ds_read_b128 v[170:173], v170 offset:3072
	s_add_i32 m0, s3, 0xc000
	ds_read_b128 v[178:181], v149
	ds_read_b128 v[182:185], v149 offset:1024
	ds_read_b128 v[186:189], v149 offset:2048
	ds_read_b128 v[190:193], v149 offset:3072
	ds_read_b128 v[194:197], v149 offset:4096
	ds_read_b128 v[198:201], v149 offset:5120
	ds_read_b128 v[202:205], v149 offset:6144
	ds_read_b128 v[206:209], v149 offset:7168
	global_load_lds_dwordx4 v134, s[40:41]
	s_add_i32 m0, s3, 0xe000
	s_nop 0
	global_load_lds_dwordx4 v136, s[40:41]
	s_waitcnt vmcnt(8)
	s_waitcnt lgkmcnt(0)
	s_barrier
	s_setprio 1
	s_waitcnt lgkmcnt(0)
	v_mfma_f32_16x16x32_bf16 v[124:127], v[138:141], v[178:181], 0
	v_mfma_f32_16x16x32_bf16 v[120:123], v[150:153], v[178:181], 0
	v_mfma_f32_16x16x32_bf16 v[108:111], v[138:141], v[186:189], 0
	v_mfma_f32_16x16x32_bf16 v[104:107], v[150:153], v[186:189], 0
	v_mfma_f32_16x16x32_bf16 v[92:95], v[138:141], v[194:197], 0
	v_mfma_f32_16x16x32_bf16 v[88:91], v[150:153], v[194:197], 0
	v_mfma_f32_16x16x32_bf16 v[76:79], v[138:141], v[202:205], 0
	v_mfma_f32_16x16x32_bf16 v[72:75], v[150:153], v[202:205], 0
	v_mfma_f32_16x16x32_bf16 v[124:127], v[142:145], v[182:185], v[124:127]
	v_mfma_f32_16x16x32_bf16 v[120:123], v[154:157], v[182:185], v[120:123]
	v_mfma_f32_16x16x32_bf16 v[108:111], v[142:145], v[190:193], v[108:111]
	v_mfma_f32_16x16x32_bf16 v[104:107], v[154:157], v[190:193], v[104:107]
	v_mfma_f32_16x16x32_bf16 v[92:95], v[142:145], v[198:201], v[92:95]
	v_mfma_f32_16x16x32_bf16 v[88:91], v[154:157], v[198:201], v[88:91]
	v_mfma_f32_16x16x32_bf16 v[76:79], v[142:145], v[206:209], v[76:79]
	v_mfma_f32_16x16x32_bf16 v[72:75], v[154:157], v[206:209], v[72:75]
	s_setprio 0
	s_setprio 1
	v_mfma_f32_16x16x32_bf16 v[116:119], v[158:161], v[178:181], 0
	v_mfma_f32_16x16x32_bf16 v[112:115], v[166:169], v[178:181], 0
	v_mfma_f32_16x16x32_bf16 v[100:103], v[158:161], v[186:189], 0
	v_mfma_f32_16x16x32_bf16 v[96:99], v[166:169], v[186:189], 0
	v_mfma_f32_16x16x32_bf16 v[84:87], v[158:161], v[194:197], 0
	v_mfma_f32_16x16x32_bf16 v[80:83], v[166:169], v[194:197], 0
	v_mfma_f32_16x16x32_bf16 v[68:71], v[158:161], v[202:205], 0
	v_mfma_f32_16x16x32_bf16 v[64:67], v[166:169], v[202:205], 0
	v_mfma_f32_16x16x32_bf16 v[116:119], v[162:165], v[182:185], v[116:119]
	v_mfma_f32_16x16x32_bf16 v[112:115], v[170:173], v[182:185], v[112:115]
	v_mfma_f32_16x16x32_bf16 v[100:103], v[162:165], v[190:193], v[100:103]
	v_mfma_f32_16x16x32_bf16 v[96:99], v[170:173], v[190:193], v[96:99]
	v_mfma_f32_16x16x32_bf16 v[84:87], v[162:165], v[198:201], v[84:87]
	v_mfma_f32_16x16x32_bf16 v[80:83], v[170:173], v[198:201], v[80:83]
	v_mfma_f32_16x16x32_bf16 v[68:71], v[162:165], v[206:209], v[68:71]
	v_mfma_f32_16x16x32_bf16 v[64:67], v[170:173], v[206:209], v[64:67]
	s_setprio 0
	s_barrier
	s_add_i32 s55, s55, s2
	s_mov_b32 m0, s55
	ds_read_b128 v[178:181], v149 offset:16384
	ds_read_b128 v[182:185], v149 offset:17408
	ds_read_b128 v[186:189], v149 offset:18432
	ds_read_b128 v[190:193], v149 offset:19456
	ds_read_b128 v[194:197], v149 offset:20480
	ds_read_b128 v[198:201], v149 offset:21504
	ds_read_b128 v[202:205], v149 offset:22528
	ds_read_b128 v[206:209], v149 offset:23552
	global_load_lds_dwordx4 v176, s[48:49]
	s_add_i32 m0, s55, 0x2000
	s_add_u32 s56, s48, 0x80000
	s_addc_u32 s57, s49, 0
	s_add_i32 s55, s58, s2
	global_load_lds_dwordx4 v132, s[48:49]
	s_mov_b32 m0, s55
	v_lshl_add_u64 v[214:215], s[50:51], 0, v[130:131]
	global_load_lds_dwordx4 v176, s[56:57]
	s_add_i32 m0, s55, 0x2000
	s_nop 0
	global_load_lds_dwordx4 v132, s[56:57]
	v_lshl_add_u64 v[212:213], s[50:51], 0, v[128:129]
	s_mov_b32 m0, s3
	s_nop 0
	global_load_lds_dwordx4 v[212:213], off
	s_mov_b32 m0, s22
	s_nop 0
	global_load_lds_dwordx4 v[214:215], off
	s_waitcnt vmcnt(8)
	s_waitcnt lgkmcnt(0)
	s_barrier
; #define PG8_STAGE(bufoff, gbase, voff) do { _Pragma("unroll") for (int _i = 0; _i < 2; ++_i) \
;         __builtin_amdgcn_global_load_lds((const unsigned*)((const char*)(gbase) + (voff)[_i]), (PG8_LAS unsigned*)(lds + (bufoff) + ldsw + _i * 8192), 16, 0, 0); } while (0)
; #define PG8_LDA(dst, b, h) do { _Pragma("unroll") for (int m = 0; m < 4; ++m) _Pragma("unroll") for (int k = 0; k < 2; ++k) dst[m][k] = *(const PG8_LAS bf16x8*)(lds + PG8_SA(b, h) + aoff + m * 2048 + k * 1024); } while (0)
; #define PG8_LDB(dst, b, h) do { _Pragma("unroll") for (int n = 0; n < 2; ++n) _Pragma("unroll") for (int k = 0; k < 2; ++k) dst[n][k] = *(const PG8_LAS bf16x8*)(lds + PG8_SB(b, h) + boff + n * 2048 + k * 1024); } while (0)
; #define PG8_MMA(ai, bj, At, Bt) do { __builtin_amdgcn_s_setprio(1); _Pragma("unroll") for (int m = 0; m < 4; ++m) _Pragma("unroll") for (int n = 0; n < 2; ++n) _Pragma("unroll") for (int k = 0; k < 2; ++k) \
;         acc[ai][bj][m][n] = __builtin_amdgcn_mfma_f32_16x16x32_bf16(Bt[n][k], At[m][k], acc[ai][bj][m][n], 0, 0, 0); __builtin_amdgcn_s_setprio(0); } while (0)
; #define PG8_WAIT_V(n) asm volatile("s_waitcnt vmcnt(" #n ")" ::: "memory")
; #define PG8_WAIT_L(n) asm volatile("s_waitcnt lgkmcnt(" #n ")" ::: "memory")
; #define PG8_BAR __builtin_amdgcn_s_barrier()
; #define PG8_SCHED __builtin_amdgcn_sched_barrier(0)
; template <class Epi, class Sched, bool ALIGN_EPI = false, bool SP2 = false>
; __device__ __forceinline__ void gemm_phase(PG8_LAS unsigned char* lds, const Gemm g, const Sched& S, const Epi& E, int wv) {
;     ...
;             PG8_WAIT_V(8); PG8_WAIT_L(0); PG8_BAR; PG8_MMA(0, 0, At, B0); PG8_MMA(0, 1, At, B1); PG8_BAR; PG8_SCHED;
;             PG8_LDA(At, 0, 1); PG8_STAGE(PG8_SB(0, 0), b2, voffB); PG8_STAGE(PG8_SB(0, 1), b2 + hstep, voffB); PG8_STAGE(PG8_SA(0, 0), a2, voffA);
;             PG8_WAIT_V(8); PG8_WAIT_L(0); PG8_BAR; PG8_MMA(1, 0, At, B0); PG8_MMA(1, 1, At, B1); PG8_BAR; PG8_SCHED;
;             PG8_LDB(B0, 1, 0); PG8_LDB(B1, 1, 1); PG8_SCHED; PG8_LDA(At, 1, 0); PG8_STAGE(PG8_SA(0, 1), a2 + hstep, voffA);
;             PG8_WAIT_V(8); PG8_WAIT_L(0); PG8_BAR; PG8_MMA(0, 0, At, B0); PG8_MMA(0, 1, At, B1); PG8_BAR; PG8_SCHED;
	s_setprio 1
	s_waitcnt lgkmcnt(0)
	v_mfma_f32_16x16x32_bf16 v[60:63], v[138:141], v[178:181], 0
	v_mfma_f32_16x16x32_bf16 v[56:59], v[150:153], v[178:181], 0
	v_mfma_f32_16x16x32_bf16 v[44:47], v[138:141], v[186:189], 0
	v_mfma_f32_16x16x32_bf16 v[40:43], v[150:153], v[186:189], 0
	v_mfma_f32_16x16x32_bf16 v[28:31], v[138:141], v[194:197], 0
	v_mfma_f32_16x16x32_bf16 v[24:27], v[150:153], v[194:197], 0
	v_mfma_f32_16x16x32_bf16 v[12:15], v[138:141], v[202:205], 0
	v_mfma_f32_16x16x32_bf16 v[8:11], v[150:153], v[202:205], 0
	v_mfma_f32_16x16x32_bf16 v[60:63], v[142:145], v[182:185], v[60:63]
	v_mfma_f32_16x16x32_bf16 v[56:59], v[154:157], v[182:185], v[56:59]
	v_mfma_f32_16x16x32_bf16 v[44:47], v[142:145], v[190:193], v[44:47]
	v_mfma_f32_16x16x32_bf16 v[40:43], v[154:157], v[190:193], v[40:43]
	v_mfma_f32_16x16x32_bf16 v[28:31], v[142:145], v[198:201], v[28:31]
	v_mfma_f32_16x16x32_bf16 v[24:27], v[154:157], v[198:201], v[24:27]
	v_mfma_f32_16x16x32_bf16 v[12:15], v[142:145], v[206:209], v[12:15]
	v_mfma_f32_16x16x32_bf16 v[8:11], v[154:157], v[206:209], v[8:11]
	s_setprio 0
	s_setprio 1
	v_mfma_f32_16x16x32_bf16 v[52:55], v[158:161], v[178:181], 0
	v_mfma_f32_16x16x32_bf16 v[48:51], v[166:169], v[178:181], 0
	v_mfma_f32_16x16x32_bf16 v[36:39], v[158:161], v[186:189], 0
	v_mfma_f32_16x16x32_bf16 v[32:35], v[166:169], v[186:189], 0
	v_mfma_f32_16x16x32_bf16 v[20:23], v[158:161], v[194:197], 0
	v_mfma_f32_16x16x32_bf16 v[16:19], v[166:169], v[194:197], 0
	v_mfma_f32_16x16x32_bf16 v[4:7], v[158:161], v[202:205], 0
	v_mfma_f32_16x16x32_bf16 v[0:3], v[166:169], v[202:205], 0
	v_mfma_f32_16x16x32_bf16 v[52:55], v[162:165], v[182:185], v[52:55]
	v_mfma_f32_16x16x32_bf16 v[48:51], v[170:173], v[182:185], v[48:51]
	v_mfma_f32_16x16x32_bf16 v[36:39], v[162:165], v[190:193], v[36:39]
	v_mfma_f32_16x16x32_bf16 v[32:35], v[170:173], v[190:193], v[32:35]
	v_mfma_f32_16x16x32_bf16 v[20:23], v[162:165], v[198:201], v[20:23]
	v_mfma_f32_16x16x32_bf16 v[16:19], v[170:173], v[198:201], v[16:19]
	v_mfma_f32_16x16x32_bf16 v[4:7], v[162:165], v[206:209], v[4:7]
	v_mfma_f32_16x16x32_bf16 v[0:3], v[170:173], v[206:209], v[0:3]
	s_setprio 0
	s_barrier
	s_add_i32 s55, 0, 0x18000
	s_add_i32 s56, 0, 0x1c000
	v_add_u32_e32 v154, s55, v147
	v_add_u32_e32 v170, s56, v147
	ds_read_b128 v[138:141], v154
	ds_read_b128 v[142:145], v154 offset:1024
	ds_read_b128 v[150:153], v154 offset:2048
	ds_read_b128 v[154:157], v154 offset:3072
	ds_read_b128 v[158:161], v170
	ds_read_b128 v[162:165], v170 offset:1024
	ds_read_b128 v[166:169], v170 offset:2048
	ds_read_b128 v[170:173], v170 offset:3072
	s_add_u32 s50, s50, 0x80000
	s_addc_u32 s51, s51, 0
	s_mov_b32 m0, s23
	ds_read_b128 v[178:181], v149 offset:32768
	ds_read_b128 v[182:185], v149 offset:33792
	ds_read_b128 v[186:189], v149 offset:34816
	ds_read_b128 v[190:193], v149 offset:35840
	ds_read_b128 v[194:197], v149 offset:36864
	ds_read_b128 v[198:201], v149 offset:37888
	ds_read_b128 v[202:205], v149 offset:38912
	ds_read_b128 v[206:209], v149 offset:39936
	global_load_lds_dwordx4 v128, s[50:51]
	v_lshl_add_u64 v[216:217], s[50:51], 0, v[130:131]
	s_mov_b32 m0, s24
	s_nop 0
	global_load_lds_dwordx4 v[216:217], off
	s_waitcnt vmcnt(8)
	s_waitcnt lgkmcnt(0)
	s_barrier
	s_setprio 1
	s_waitcnt lgkmcnt(0)
	v_mfma_f32_16x16x32_bf16 v[124:127], v[138:141], v[178:181], v[124:127]
	v_mfma_f32_16x16x32_bf16 v[120:123], v[150:153], v[178:181], v[120:123]
	v_mfma_f32_16x16x32_bf16 v[108:111], v[138:141], v[186:189], v[108:111]
	v_mfma_f32_16x16x32_bf16 v[104:107], v[150:153], v[186:189], v[104:107]
	v_mfma_f32_16x16x32_bf16 v[92:95], v[138:141], v[194:197], v[92:95]
	v_mfma_f32_16x16x32_bf16 v[88:91], v[150:153], v[194:197], v[88:91]
	v_mfma_f32_16x16x32_bf16 v[76:79], v[138:141], v[202:205], v[76:79]
	v_mfma_f32_16x16x32_bf16 v[72:75], v[150:153], v[202:205], v[72:75]
	v_mfma_f32_16x16x32_bf16 v[124:127], v[142:145], v[182:185], v[124:127]
	v_mfma_f32_16x16x32_bf16 v[120:123], v[154:157], v[182:185], v[120:123]
	v_mfma_f32_16x16x32_bf16 v[108:111], v[142:145], v[190:193], v[108:111]
	v_mfma_f32_16x16x32_bf16 v[104:107], v[154:157], v[190:193], v[104:107]
	v_mfma_f32_16x16x32_bf16 v[92:95], v[142:145], v[198:201], v[92:95]
	v_mfma_f32_16x16x32_bf16 v[88:91], v[154:157], v[198:201], v[88:91]
	v_mfma_f32_16x16x32_bf16 v[76:79], v[142:145], v[206:209], v[76:79]
	v_mfma_f32_16x16x32_bf16 v[72:75], v[154:157], v[206:209], v[72:75]
	s_setprio 0
	s_setprio 1
	v_mfma_f32_16x16x32_bf16 v[116:119], v[158:161], v[178:181], v[116:119]
	v_mfma_f32_16x16x32_bf16 v[112:115], v[166:169], v[178:181], v[112:115]
	v_mfma_f32_16x16x32_bf16 v[100:103], v[158:161], v[186:189], v[100:103]
	v_mfma_f32_16x16x32_bf16 v[96:99], v[166:169], v[186:189], v[96:99]
	v_mfma_f32_16x16x32_bf16 v[84:87], v[158:161], v[194:197], v[84:87]
	v_mfma_f32_16x16x32_bf16 v[80:83], v[166:169], v[194:197], v[80:83]
	v_mfma_f32_16x16x32_bf16 v[68:71], v[158:161], v[202:205], v[68:71]
	v_mfma_f32_16x16x32_bf16 v[64:67], v[166:169], v[202:205], v[64:67]
	v_mfma_f32_16x16x32_bf16 v[116:119], v[162:165], v[182:185], v[116:119]
	v_mfma_f32_16x16x32_bf16 v[112:115], v[170:173], v[182:185], v[112:115]
	v_mfma_f32_16x16x32_bf16 v[100:103], v[162:165], v[190:193], v[100:103]
	v_mfma_f32_16x16x32_bf16 v[96:99], v[170:173], v[190:193], v[96:99]
	v_mfma_f32_16x16x32_bf16 v[84:87], v[162:165], v[198:201], v[84:87]
	v_mfma_f32_16x16x32_bf16 v[80:83], v[170:173], v[198:201], v[80:83]
	v_mfma_f32_16x16x32_bf16 v[68:71], v[162:165], v[206:209], v[68:71]
	v_mfma_f32_16x16x32_bf16 v[64:67], v[170:173], v[206:209], v[64:67]
	s_setprio 0
	s_barrier
; #define PG8_STAGE(bufoff, gbase, voff) do { _Pragma("unroll") for (int _i = 0; _i < 2; ++_i) \
;         __builtin_amdgcn_global_load_lds((const unsigned*)((const char*)(gbase) + (voff)[_i]), (PG8_LAS unsigned*)(lds + (bufoff) + ldsw + _i * 8192), 16, 0, 0); } while (0)
; #define PG8_LDA(dst, b, h) do { _Pragma("unroll") for (int m = 0; m < 4; ++m) _Pragma("unroll") for (int k = 0; k < 2; ++k) dst[m][k] = *(const PG8_LAS bf16x8*)(lds + PG8_SA(b, h) + aoff + m * 2048 + k * 1024); } while (0)
; #define PG8_MMA(ai, bj, At, Bt) do { __builtin_amdgcn_s_setprio(1); _Pragma("unroll") for (int m = 0; m < 4; ++m) _Pragma("unroll") for (int n = 0; n < 2; ++n) _Pragma("unroll") for (int k = 0; k < 2; ++k) \
;         acc[ai][bj][m][n] = __builtin_amdgcn_mfma_f32_16x16x32_bf16(Bt[n][k], At[m][k], acc[ai][bj][m][n], 0, 0, 0); __builtin_amdgcn_s_setprio(0); } while (0)
; #define PG8_WAIT_V(n) asm volatile("s_waitcnt vmcnt(" #n ")" ::: "memory")
; #define PG8_WAIT_L(n) asm volatile("s_waitcnt lgkmcnt(" #n ")" ::: "memory")
; #define PG8_BAR __builtin_amdgcn_s_barrier()
; #define PG8_SCHED __builtin_amdgcn_sched_barrier(0)
; template <class Epi, class Sched, bool ALIGN_EPI = false, bool SP2 = false>
; __device__ __forceinline__ void gemm_phase(PG8_LAS unsigned char* lds, const Gemm g, const Sched& S, const Epi& E, int wv) {
;     ...
;         for (int t = 0; t < nt; t += 2) {
;             const bool last = (t == nt - 2);
;             const char* a1 = cA + (size_t)(t + 1) * kstep;
;     ...
;             PG8_LDA(At, 1, 1); PG8_STAGE(PG8_SB(1, 0), b3, voffB); PG8_STAGE(PG8_SB(1, 1), b3 + hstep, voffB); PG8_STAGE(PG8_SA(1, 0), a3, voffA);
;             PG8_WAIT_V(8); PG8_WAIT_L(0); PG8_BAR; PG8_MMA(1, 0, At, B0); PG8_MMA(1, 1, At, B1); PG8_BAR; PG8_SCHED;
	s_add_i32 s50, s55, s2
	s_add_u32 s100, s48, s28
	s_addc_u32 s101, s49, s29
	s_mov_b32 m0, s50
	ds_read_b128 v[178:181], v149 offset:49152
	ds_read_b128 v[182:185], v149 offset:50176
	ds_read_b128 v[186:189], v149 offset:51200
	ds_read_b128 v[190:193], v149 offset:52224
	ds_read_b128 v[194:197], v149 offset:53248
	ds_read_b128 v[198:201], v149 offset:54272
	ds_read_b128 v[202:205], v149 offset:55296
	ds_read_b128 v[206:209], v149 offset:56320
	global_load_lds_dwordx4 v176, s[100:101]
	s_add_i32 m0, s50, 0x2000
	s_add_u32 s48, s48, 0x80080
	s_addc_u32 s49, s49, 0
	s_add_i32 s50, s56, s2
	global_load_lds_dwordx4 v132, s[100:101]
	s_mov_b32 m0, s50
	s_nop 0
	global_load_lds_dwordx4 v176, s[48:49]
	s_add_i32 m0, s50, 0x2000
	s_nop 0
	global_load_lds_dwordx4 v132, s[48:49]
	v_lshl_add_u64 v[174:175], v[212:213], 0, s[28:29]
	s_mov_b32 m0, s27
	s_nop 0
	global_load_lds_dwordx4 v[174:175], off
	v_lshl_add_u64 v[174:175], v[214:215], 0, s[28:29]
	s_mov_b32 m0, s30
	s_nop 0
	global_load_lds_dwordx4 v[174:175], off
	s_waitcnt vmcnt(8)
	s_waitcnt lgkmcnt(0)
	s_barrier
	s_setprio 1
	s_waitcnt lgkmcnt(0)
	v_mfma_f32_16x16x32_bf16 v[60:63], v[138:141], v[178:181], v[60:63]
	v_mfma_f32_16x16x32_bf16 v[56:59], v[150:153], v[178:181], v[56:59]
	v_mfma_f32_16x16x32_bf16 v[44:47], v[138:141], v[186:189], v[44:47]
	v_mfma_f32_16x16x32_bf16 v[40:43], v[150:153], v[186:189], v[40:43]
	v_mfma_f32_16x16x32_bf16 v[28:31], v[138:141], v[194:197], v[28:31]
	v_mfma_f32_16x16x32_bf16 v[24:27], v[150:153], v[194:197], v[24:27]
	v_mfma_f32_16x16x32_bf16 v[12:15], v[138:141], v[202:205], v[12:15]
	v_mfma_f32_16x16x32_bf16 v[8:11], v[150:153], v[202:205], v[8:11]
	v_mfma_f32_16x16x32_bf16 v[60:63], v[142:145], v[182:185], v[60:63]
	v_mfma_f32_16x16x32_bf16 v[56:59], v[154:157], v[182:185], v[56:59]
	v_mfma_f32_16x16x32_bf16 v[44:47], v[142:145], v[190:193], v[44:47]
	v_mfma_f32_16x16x32_bf16 v[40:43], v[154:157], v[190:193], v[40:43]
	v_mfma_f32_16x16x32_bf16 v[28:31], v[142:145], v[198:201], v[28:31]
	v_mfma_f32_16x16x32_bf16 v[24:27], v[154:157], v[198:201], v[24:27]
	v_mfma_f32_16x16x32_bf16 v[12:15], v[142:145], v[206:209], v[12:15]
	v_mfma_f32_16x16x32_bf16 v[8:11], v[154:157], v[206:209], v[8:11]
	s_setprio 0
	s_setprio 1
	v_mfma_f32_16x16x32_bf16 v[52:55], v[158:161], v[178:181], v[52:55]
	v_mfma_f32_16x16x32_bf16 v[48:51], v[166:169], v[178:181], v[48:51]
	v_mfma_f32_16x16x32_bf16 v[36:39], v[158:161], v[186:189], v[36:39]
	v_mfma_f32_16x16x32_bf16 v[32:35], v[166:169], v[186:189], v[32:35]
	v_mfma_f32_16x16x32_bf16 v[20:23], v[158:161], v[194:197], v[20:23]
	v_mfma_f32_16x16x32_bf16 v[16:19], v[166:169], v[194:197], v[16:19]
	v_mfma_f32_16x16x32_bf16 v[4:7], v[158:161], v[202:205], v[4:7]
	v_mfma_f32_16x16x32_bf16 v[0:3], v[166:169], v[202:205], v[0:3]
	v_mfma_f32_16x16x32_bf16 v[52:55], v[162:165], v[182:185], v[52:55]
	v_mfma_f32_16x16x32_bf16 v[48:51], v[170:173], v[182:185], v[48:51]
	v_mfma_f32_16x16x32_bf16 v[36:39], v[162:165], v[190:193], v[36:39]
	v_mfma_f32_16x16x32_bf16 v[32:35], v[170:173], v[190:193], v[32:35]
	v_mfma_f32_16x16x32_bf16 v[20:23], v[162:165], v[198:201], v[20:23]
	v_mfma_f32_16x16x32_bf16 v[16:19], v[170:173], v[198:201], v[16:19]
	v_mfma_f32_16x16x32_bf16 v[4:7], v[162:165], v[206:209], v[4:7]
	v_mfma_f32_16x16x32_bf16 v[0:3], v[170:173], v[206:209], v[0:3]
	s_setprio 0
	s_barrier
	s_add_i32 s54, s54, 2
	s_add_u32 s40, s40, 0x100
	s_addc_u32 s41, s41, 0
	s_add_u32 s52, s52, 0x100
	s_addc_u32 s53, s53, 0
	s_cmp_gt_u32 s54, 29
